# conv phase remapped XCD-aligned + XCD-local barrier conv->conv-out GEMM
# speedup vs baseline: 1.0001x; 1.0001x over previous
.LBB0_771:
	s_mov_b64 s[40:41], s[92:93]
	s_cmp_ge_i32 s2, s40
	s_cselect_b64 s[4:5], -1, 0
	s_cmp_lt_i32 s2, s41
	s_cselect_b64 s[2:3], -1, 0
	s_and_b64 s[2:3], s[4:5], s[2:3]
	s_andn2_b64 vcc, exec, s[2:3]
	s_mov_b64 s[42:43], s[94:95]
	s_cbranch_vccnz .LBB0_834
	v_readlane_b32 s18, v255, 16
	v_readlane_b32 s28, v255, 20
	v_readlane_b32 s56, v255, 41
	s_andn2_b64 vcc, exec, s[62:63]
	v_readlane_b32 s19, v255, 17
	v_readlane_b32 s29, v255, 21
	v_readlane_b32 s57, v255, 42
	s_mov_b64 s[62:63], 0x180000
	s_mov_b64 s[64:65], 0x1000
	s_mov_b64 s[66:67], 0x2000
	v_mov_b32_e32 v0, 0x2080c
	ds_read_b32 v0, v0
	s_waitcnt lgkmcnt(0)
	v_readfirstlane_b32 s100, v0
	s_and_b32 s101, s100, 7
	s_lshr_b32 s100, s100, 3
	s_mul_i32 s101, s101, 0x30000
	s_lshl_b32 s100, s100, 9
	s_add_u32 s100, s100, s101
	s_add_u32 s62, s101, 0x30000
	s_mov_b32 s63, 0
	s_mov_b64 s[18:19], 0x4000
	s_mov_b64 s[28:29], 0x8000
	s_mov_b64 s[56:57], 0x40000
	s_cbranch_vccnz .LBB0_822
	s_waitcnt vmcnt(0)
	s_barrier
	s_mov_b64 s[40:41], exec
	v_readlane_b32 s2, v254, 0
	v_readlane_b32 s3, v254, 1
	s_and_b64 s[2:3], s[40:41], s[2:3]
	s_mov_b64 exec, s[2:3]
	s_cbranch_execz .LBB0_821
	v_readlane_b32 s2, v255, 34
	s_waitcnt vmcnt(0) expcnt(0) lgkmcnt(0)
	s_nop 0
	v_mov_b32_e32 v0, s2
	ds_read_b32 v2, v0
	v_readlane_b32 s2, v255, 35
	s_waitcnt lgkmcnt(0)
	v_cmp_ne_u32_e32 vcc, 0, v2
	v_mov_b32_e32 v0, s2
	ds_read_b32 v0, v0
	s_cbranch_vccnz .LBB0_789
	s_mov_b32 s2, 1
	s_branch .LBB0_777

.LBB0_822:
	s_mov_b64 s[42:43], s[88:89]
	s_waitcnt vmcnt(0)
	v_mov_b32_e32 v0, v204
	s_mov_b32 s2, s100
	s_mov_b32 s3, 0
	v_ashrrev_i32_e32 v1, 31, v0
	s_waitcnt vmcnt(2)
	v_lshl_add_u64 v[36:37], s[2:3], 0, v[0:1]
	v_cmp_gt_i64_e32 vcc, s[62:63], v[36:37]
	s_and_saveexec_b64 s[40:41], vcc
	s_cbranch_execz .LBB0_833
	s_load_dwordx2 s[2:3], s[42:43], 0xb8
	v_readlane_b32 s4, v255, 53
	v_readlane_b32 s5, v255, 54
	s_and_b64 s[4:5], s[4:5], exec
	s_mul_i32 s10, s100, 8
	s_load_dwordx2 s[4:5], s[42:43], 0x58
	s_mov_b32 s11, 0
	s_mov_b64 s[50:51], 0
	s_nop 0
	v_lshl_add_u64 v[38:39], v[0:1], 3, s[10:11]
	s_cselect_b32 s10, 0x3000, 0
	s_waitcnt lgkmcnt(0)
	s_add_u32 s42, s2, 0xb7c8000
	s_addc_u32 s43, s3, 0
	s_add_u32 s44, s2, 0xcfc8000
	s_addc_u32 s45, s3, 0
	s_add_u32 s46, s4, s10
	s_addc_u32 s47, s5, 0
	s_add_u32 s48, s2, 0x9fc8000
	s_addc_u32 s49, s3, 0
	s_branch .LBB0_825
.LBB0_824:
	s_or_b64 exec, exec, s[52:53]
	v_ashrrev_i64 v[20:21], 22, v[20:21]
	s_waitcnt vmcnt(1)
	v_lshlrev_b32_e32 v71, 16, v28
	v_and_b32_e32 v72, 0xffff0000, v28
	v_lshlrev_b32_e32 v73, 16, v29
	v_and_b32_e32 v74, 0xffff0000, v29
	v_lshlrev_b32_e32 v28, 2, v32
	v_mov_b32_e32 v29, v97
	v_lshl_add_u64 v[20:21], v[20:21], 1, s[42:43]
	v_mov_b32_e32 v43, v97
	v_lshl_add_u64 v[32:33], s[46:47], 0, v[28:29]
	v_lshl_add_u64 v[20:21], v[20:21], 0, v[42:43]
	v_add_co_u32_e32 v34, vcc, s24, v32
	global_load_dwordx4 v[20:23], v[20:21], off
	v_lshlrev_b32_e32 v49, 16, v24
	v_and_b32_e32 v66, 0xffff0000, v24
	v_lshlrev_b32_e32 v67, 16, v25
	v_and_b32_e32 v68, 0xffff0000, v25
	v_lshlrev_b32_e32 v69, 16, v26
	v_and_b32_e32 v70, 0xffff0000, v26
	v_lshlrev_b32_e32 v48, 16, v27
	v_and_b32_e32 v45, 0xffff0000, v27
	global_load_dwordx4 v[24:27], v28, s[46:47] offset:16
	global_load_dwordx4 v[50:53], v28, s[46:47]
	v_lshl_add_u64 v[28:29], v[32:33], 0, s[64:65]
	v_addc_co_u32_e32 v35, vcc, 0, v33, vcc
	v_lshl_add_u64 v[32:33], v[32:33], 0, s[66:67]
	v_lshlrev_b32_e32 v75, 16, v30
	v_and_b32_e32 v76, 0xffff0000, v30
	v_lshlrev_b32_e32 v47, 16, v31
	v_and_b32_e32 v46, 0xffff0000, v31
	global_load_dwordx4 v[54:57], v[34:35], off offset:-4096
	s_nop 0
	global_load_dwordx4 v[28:31], v[28:29], off offset:16
	s_nop 0
	global_load_dwordx4 v[58:61], v[34:35], off
	s_nop 0
	global_load_dwordx4 v[32:35], v[32:33], off offset:16
	v_lshlrev_b32_e32 v63, 16, v12
	v_lshlrev_b32_e32 v62, 16, v8
	v_lshl_add_u64 v[36:37], v[36:37], 0, s[28:29]
	s_sub_u32 s2, s62, 1
	s_mov_b32 s3, 0
	s_waitcnt vmcnt(4)
	v_mov_b32_e32 v64, v50
	s_waitcnt vmcnt(1)
	v_mov_b32_e32 v65, v58
	v_pk_mul_f32 v[62:63], v[64:65], v[62:63]
	v_mov_b32_e32 v58, v51
	v_fma_f32 v49, v54, v49, v62
	v_add_f32_e32 v49, v49, v63
	v_and_b32_e32 v63, 0xffff0000, v12
	v_and_b32_e32 v62, 0xffff0000, v8
	v_pk_mul_f32 v[50:51], v[58:59], v[62:63]
	v_mov_b32_e32 v54, v52
	v_fma_f32 v8, v55, v66, v50
	v_add_f32_e32 v8, v8, v51
	v_lshlrev_b32_e32 v50, 16, v9
	v_lshlrev_b32_e32 v51, 16, v13
	v_mov_b32_e32 v55, v60
	v_pk_mul_f32 v[50:51], v[54:55], v[50:51]
	v_mul_f32_e32 v58, v8, v72
	v_fma_f32 v8, v56, v67, v50
	v_add_f32_e32 v8, v8, v51
	v_and_b32_e32 v13, 0xffff0000, v13
	v_and_b32_e32 v12, 0xffff0000, v9
	v_mov_b32_e32 v60, v53
	v_mul_f32_e32 v50, v8, v73
	v_pk_mul_f32 v[8:9], v[60:61], v[12:13]
	v_mov_b32_e32 v12, v24
	v_fma_f32 v8, v57, v68, v8
	v_add_f32_e32 v8, v8, v9
	v_mul_f32_e32 v51, v8, v74
	v_lshlrev_b32_e32 v9, 16, v14
	v_lshlrev_b32_e32 v8, 16, v10
	s_waitcnt vmcnt(0)
	v_mov_b32_e32 v13, v32
	v_pk_mul_f32 v[8:9], v[12:13], v[8:9]
	v_mov_b32_e32 v32, v25
	v_fma_f32 v8, v28, v69, v8
	v_add_f32_e32 v8, v8, v9
	v_mul_f32_e32 v24, v8, v75
	v_and_b32_e32 v9, 0xffff0000, v14
	v_and_b32_e32 v8, 0xffff0000, v10
	v_pk_mul_f32 v[8:9], v[32:33], v[8:9]
	v_mov_b32_e32 v12, v26
	v_fma_f32 v8, v29, v70, v8
	v_add_f32_e32 v8, v8, v9
	v_mul_f32_e32 v10, v8, v76
	v_lshlrev_b32_e32 v8, 16, v11
	v_lshlrev_b32_e32 v9, 16, v15
	v_mov_b32_e32 v13, v34
	v_pk_mul_f32 v[8:9], v[12:13], v[8:9]
	v_mov_b32_e32 v34, v27
	v_fma_f32 v8, v30, v48, v8
	v_add_f32_e32 v8, v8, v9
	v_mul_f32_e32 v12, v8, v47
	v_and_b32_e32 v9, 0xffff0000, v15
	v_and_b32_e32 v8, 0xffff0000, v11
	v_pk_mul_f32 v[8:9], v[34:35], v[8:9]
	v_mul_f32_e32 v49, v49, v71
	v_fma_f32 v8, v31, v45, v8
	v_add_f32_e32 v8, v8, v9
	v_mul_f32_e32 v11, v8, v46
	v_cvt_pk_bf16_f32 v8, v49, v58
	v_cvt_pk_bf16_f32 v9, v50, v51
	v_cvt_pk_bf16_f32 v10, v24, v10
	v_cvt_pk_bf16_f32 v11, v12, v11
	v_and_b32_e32 v13, 0x7fffffff, v39
	v_and_b32_e32 v12, 0xfffffc00, v38
	v_lshl_add_u64 v[12:13], v[12:13], 1, s[48:49]
	v_lshl_add_u64 v[12:13], v[12:13], 0, v[96:97]
	v_lshlrev_b32_e32 v96, 2, v44
	v_lshlrev_b32_e32 v45, 16, v16
	v_and_b32_e32 v46, 0xffff0000, v16
	v_lshlrev_b32_e32 v47, 16, v17
	v_and_b32_e32 v48, 0xffff0000, v17
	v_lshl_add_u64 v[16:17], s[46:47], 0, v[96:97]
	global_store_dwordx4 v[12:13], v[8:11], off
	v_lshlrev_b32_e32 v49, 16, v18
	v_and_b32_e32 v50, 0xffff0000, v18
	v_add_co_u32_e32 v18, vcc, s24, v16
	v_lshlrev_b32_e32 v51, 16, v19
	v_and_b32_e32 v52, 0xffff0000, v19
	v_lshlrev_b32_e32 v53, 16, v20
	v_and_b32_e32 v54, 0xffff0000, v20
	v_lshlrev_b32_e32 v55, 16, v21
	v_and_b32_e32 v56, 0xffff0000, v21
	v_lshlrev_b32_e32 v57, 16, v22
	v_and_b32_e32 v58, 0xffff0000, v22
	v_lshlrev_b32_e32 v59, 16, v23
	v_and_b32_e32 v60, 0xffff0000, v23
	global_load_dwordx4 v[8:11], v96, s[46:47] offset:16
	global_load_dwordx4 v[20:23], v96, s[46:47]
	v_lshl_add_u64 v[12:13], v[16:17], 0, s[64:65]
	v_addc_co_u32_e32 v19, vcc, 0, v17, vcc
	v_lshl_add_u64 v[16:17], v[16:17], 0, s[66:67]
	global_load_dwordx4 v[24:27], v[18:19], off offset:-4096
	s_nop 0
	global_load_dwordx4 v[12:15], v[12:13], off offset:16
	s_nop 0
	global_load_dwordx4 v[28:31], v[18:19], off
	s_nop 0
	global_load_dwordx4 v[16:19], v[16:17], off offset:16
	v_lshlrev_b32_e32 v33, 16, v4
	v_lshlrev_b32_e32 v32, 16, v0
	v_cmp_lt_i64_e32 vcc, s[2:3], v[36:37]
	v_lshl_add_u64 v[38:39], v[38:39], 0, s[56:57]
	s_or_b64 s[50:51], vcc, s[50:51]
	s_waitcnt vmcnt(4)
	v_mov_b32_e32 v34, v20
	s_waitcnt vmcnt(1)
	v_mov_b32_e32 v35, v28
	v_pk_mul_f32 v[32:33], v[34:35], v[32:33]
	v_mov_b32_e32 v28, v21
	v_fma_f32 v20, v24, v45, v32
	v_add_f32_e32 v20, v20, v33
	v_and_b32_e32 v33, 0xffff0000, v4
	v_and_b32_e32 v32, 0xffff0000, v0
	v_mul_f32_e32 v34, v20, v53
	v_pk_mul_f32 v[20:21], v[28:29], v[32:33]
	v_mov_b32_e32 v24, v22
	v_fma_f32 v0, v25, v46, v20
	v_add_f32_e32 v0, v0, v21
	v_lshlrev_b32_e32 v20, 16, v1
	v_lshlrev_b32_e32 v21, 16, v5
	v_mov_b32_e32 v25, v30
	v_pk_mul_f32 v[20:21], v[24:25], v[20:21]
	v_mul_f32_e32 v28, v0, v54
	v_fma_f32 v0, v26, v47, v20
	v_add_f32_e32 v0, v0, v21
	v_and_b32_e32 v5, 0xffff0000, v5
	v_and_b32_e32 v4, 0xffff0000, v1
	v_mov_b32_e32 v30, v23
	v_mul_f32_e32 v20, v0, v55
	v_pk_mul_f32 v[0:1], v[30:31], v[4:5]
	v_mov_b32_e32 v4, v8
	v_fma_f32 v0, v27, v48, v0
	v_add_f32_e32 v0, v0, v1
	v_mul_f32_e32 v21, v0, v56
	v_lshlrev_b32_e32 v1, 16, v6
	v_lshlrev_b32_e32 v0, 16, v2
	s_waitcnt vmcnt(0)
	v_mov_b32_e32 v5, v16
	v_pk_mul_f32 v[0:1], v[4:5], v[0:1]
	v_mov_b32_e32 v16, v9
	v_fma_f32 v0, v12, v49, v0
	v_add_f32_e32 v0, v0, v1
	v_mul_f32_e32 v8, v0, v57
	v_and_b32_e32 v1, 0xffff0000, v6
	v_and_b32_e32 v0, 0xffff0000, v2
	v_pk_mul_f32 v[0:1], v[16:17], v[0:1]
	v_mov_b32_e32 v4, v10
	v_fma_f32 v0, v13, v50, v0
	v_add_f32_e32 v0, v0, v1
	v_mul_f32_e32 v2, v0, v58
	v_lshlrev_b32_e32 v0, 16, v3
	v_lshlrev_b32_e32 v1, 16, v7
	v_mov_b32_e32 v5, v18
	v_pk_mul_f32 v[0:1], v[4:5], v[0:1]
	v_mov_b32_e32 v18, v11
	v_fma_f32 v0, v14, v51, v0
	v_add_f32_e32 v0, v0, v1
	v_mul_f32_e32 v4, v0, v59
	v_and_b32_e32 v1, 0xffff0000, v7
	v_and_b32_e32 v0, 0xffff0000, v3
	v_pk_mul_f32 v[0:1], v[18:19], v[0:1]
	s_nop 0
	v_fma_f32 v0, v15, v52, v0
	v_add_f32_e32 v0, v0, v1
	v_mul_f32_e32 v3, v0, v60
	v_cvt_pk_bf16_f32 v0, v34, v28
	v_cvt_pk_bf16_f32 v1, v20, v21
	v_cvt_pk_bf16_f32 v2, v8, v2
	v_cvt_pk_bf16_f32 v3, v4, v3
	v_lshlrev_b64 v[4:5], 25, v[40:41]
	v_ashrrev_i64 v[4:5], 21, v[4:5]
	v_and_b32_e32 v4, 0xfffff800, v4
	v_lshl_add_u64 v[4:5], s[48:49], 0, v[4:5]
	v_lshl_add_u64 v[4:5], v[4:5], 0, v[42:43]
	global_store_dwordx4 v[4:5], v[0:3], off
	s_andn2_b64 exec, exec, s[50:51]
	s_cbranch_execz .LBB0_833

.LBB0_961:
	s_andn2_saveexec_b64 s[2:3], s[42:43]
	s_cbranch_execz .LBB0_979
	s_mov_b64 s[42:43], exec
	s_cmp_eq_u32 s36, 7
	s_cbranch_scc1 .Lxl_fout_chk
	s_cmp_eq_u32 s36, 2
	s_cbranch_scc1 .Lxl_fout_chk
	s_cmp_eq_u32 s36, 0
	s_cbranch_scc1 .Lxl_fout_chk
	s_cmp_lg_u32 s36, 6
	s_cbranch_scc1 .Lxl_fout_no
